# gMLP zv^T fragment loads non-temporal (read once per item)
# baseline (speedup 1.0000x reference)
; #define MFMA32(a, b, c) __builtin_amdgcn_mfma_f32_32x32x16_bf16((a), (b), (c), 0, 0, 0)
; __device__ __forceinline__ void phase4_gmlp(const Args& a, LAS unsigned char* lds) {
;     ...
;     for (int item = blockIdx.x; item < 256; item += gridDim.x) {
;         const int b = item >> 4, ch = item & 15;
;         const size_t tok0 = (size_t)b * 2048 + ch * 128;
;         int tid = tid0; asm volatile("" : "+v"(tid));
;         const int lane = tid & 63, r = lane & 31, h = lane >> 5;
;         __syncthreads();
;         bf16x8_t zf[2][8];
; #pragma unroll
;         for (int dt = 0; dt < 2; ++dt)
; #pragma unroll
;             for (int ks = 0; ks < 8; ++ks) zf[dt][ks] = *(const bf16x8_t*)(zvT + ((((size_t)b * 16 + ch) * 8 + g) * 64 + 32 * dt + r) * 128 + 16 * ks + 8 * h);
;         f32x16 acc[2][4];
; #pragma unroll
;         for (int tt = 0; tt < 4; ++tt) { acc[0][tt] = zero16(); acc[1][tt] = zero16();
;             __builtin_amdgcn_sched_barrier(0);
; #pragma unroll
;             for (int ks = 0; ks < 2 * tt + 2; ++ks) {
;                 const bf16x8_t wf = *(const bf16x8_t*)(Wsp + ((size_t)g * 128 + 32 * tt + r) * 128 + 16 * ks + 8 * h);
;                 acc[0][tt] = MFMA32(zf[0][ks], wf, acc[0][tt]); acc[1][tt] = MFMA32(zf[1][ks], wf, acc[1][tt]);
;             } }
.LBB0_878:
	s_and_b32 s4, s22, 15
	s_ashr_i32 s12, s22, 4
	s_lshl_b32 s23, s4, 7
	s_lshl_b32 s4, s4, 3
	s_ashr_i32 s13, s12, 31
	s_add_i32 s4, s4, s0
	v_mov_b32_e32 v178, v184
	s_lshl_b64 s[24:25], s[12:13], 13
	s_lshl_b64 s[26:27], s[4:5], 6
	s_add_u32 s4, s26, s24
	v_lshrrev_b32_e32 v2, 2, v178
	v_and_b32_e32 v181, 31, v178
	s_addc_u32 s24, s27, s25
	v_and_b32_e32 v182, 8, v2
	v_or_b32_e32 v0, s4, v181
	v_mov_b32_e32 v1, s24
	v_lshlrev_b32_e32 v128, 1, v182
	v_lshl_add_u64 v[2:3], s[2:3], 0, v[128:129]
	v_lshlrev_b64 v[0:1], 8, v[0:1]
	v_lshl_add_u64 v[4:5], v[2:3], 0, v[0:1]
	v_add_co_u32_e32 v8, vcc, s1, v4
	s_waitcnt vmcnt(0) lgkmcnt(0)
	s_nop 0
	v_addc_co_u32_e32 v9, vcc, 0, v5, vcc
	s_barrier
	v_readlane_b32 s40, v254, 12
	v_readlane_b32 s41, v254, 13
	v_add_u32_e32 v250, s15, v181
	v_mov_b32_e32 v251, 0
	v_lshl_add_u64 v[250:251], v[250:251], 2, s[40:41]
	global_load_dword v242, v[250:251], off
	global_load_dword v244, v[250:251], off offset:128
	global_load_dword v246, v[250:251], off offset:256
	global_load_dword v248, v[250:251], off offset:384
	global_load_dwordx4 v[0:3], v[4:5], off nt
	global_load_dwordx4 v[130:133], v[4:5], off offset:32 nt
	global_load_dwordx4 v[134:137], v[4:5], off offset:64 nt
	global_load_dwordx4 v[138:141], v[4:5], off offset:96 nt
	global_load_dwordx4 v[142:145], v[4:5], off offset:128 nt
	global_load_dwordx4 v[146:149], v[4:5], off offset:160 nt
	global_load_dwordx4 v[150:153], v[4:5], off offset:192 nt
	global_load_dwordx4 v[154:157], v[4:5], off offset:224 nt
	s_nop 0
	global_load_dwordx4 v[4:7], v[8:9], off nt
	global_load_dwordx4 v[158:161], v[8:9], off offset:32 nt
	global_load_dwordx4 v[170:173], v[8:9], off offset:64 nt
	global_load_dwordx4 v[174:177], v[8:9], off offset:96 nt
	global_load_dwordx4 v[186:189], v[8:9], off offset:128 nt
	global_load_dwordx4 v[190:193], v[8:9], off offset:160 nt
	global_load_dwordx4 v[194:197], v[8:9], off offset:192 nt
	global_load_dwordx4 v[198:201], v[8:9], off offset:224 nt
	s_lshl_b64 s[12:13], s[12:13], 11
	v_and_b32_e32 v183, 63, v178
	v_lshlrev_b32_e32 v8, 8, v181
	v_mov_b32_e32 v9, v129
	v_lshl_add_u64 v[10:11], s[10:11], 0, v[128:129]
	v_lshl_add_u64 v[16:17], v[10:11], 0, v[8:9]
	global_load_dwordx4 v[8:11], v[16:17], off
	global_load_dwordx4 v[12:15], v[16:17], off offset:32
	s_waitcnt vmcnt(1)
	v_mfma_f32_32x32x16_bf16 v[112:127], v[0:3], v[8:11], 0
	v_mfma_f32_32x32x16_bf16 v[96:111], v[4:7], v[8:11], 0
	s_waitcnt vmcnt(0)
	v_mfma_f32_32x32x16_bf16 v[112:127], v[130:133], v[12:15], v[112:127]
	v_mfma_f32_32x32x16_bf16 v[96:111], v[158:161], v[12:15], v[96:111]
	v_add_co_u32_e32 v18, vcc, s1, v16
	s_nop 1
	v_addc_co_u32_e32 v19, vcc, 0, v17, vcc
	global_load_dwordx4 v[8:11], v[18:19], off
	global_load_dwordx4 v[12:15], v[18:19], off offset:32
	s_waitcnt vmcnt(1)
	v_mfma_f32_32x32x16_bf16 v[80:95], v[0:3], v[8:11], 0
	v_mfma_f32_32x32x16_bf16 v[64:79], v[4:7], v[8:11], 0
	global_load_dwordx4 v[8:11], v[18:19], off offset:64
	s_waitcnt vmcnt(1)
	v_mfma_f32_32x32x16_bf16 v[80:95], v[130:133], v[12:15], v[80:95]
	v_mfma_f32_32x32x16_bf16 v[64:79], v[158:161], v[12:15], v[64:79]
	global_load_dwordx4 v[12:15], v[18:19], off offset:96
	s_waitcnt vmcnt(1)
	v_mfma_f32_32x32x16_bf16 v[80:95], v[134:137], v[8:11], v[80:95]
	v_mfma_f32_32x32x16_bf16 v[64:79], v[170:173], v[8:11], v[64:79]
	s_waitcnt vmcnt(0)
	v_mfma_f32_32x32x16_bf16 v[80:95], v[138:141], v[12:15], v[80:95]
	v_mfma_f32_32x32x16_bf16 v[64:79], v[174:177], v[12:15], v[64:79]
	v_add_co_u32_e32 v18, vcc, s16, v16
	s_nop 1
	v_addc_co_u32_e32 v19, vcc, 0, v17, vcc
	global_load_dwordx4 v[8:11], v[18:19], off
	global_load_dwordx4 v[12:15], v[18:19], off offset:32
	s_waitcnt vmcnt(1)
	v_mfma_f32_32x32x16_bf16 v[48:63], v[0:3], v[8:11], 0
	v_mfma_f32_32x32x16_bf16 v[32:47], v[4:7], v[8:11], 0
	global_load_dwordx4 v[8:11], v[18:19], off offset:64
	s_waitcnt vmcnt(1)
	v_mfma_f32_32x32x16_bf16 v[48:63], v[130:133], v[12:15], v[48:63]
	v_mfma_f32_32x32x16_bf16 v[32:47], v[158:161], v[12:15], v[32:47]
	global_load_dwordx4 v[12:15], v[18:19], off offset:96
	s_waitcnt vmcnt(1)
	v_mfma_f32_32x32x16_bf16 v[48:63], v[134:137], v[8:11], v[48:63]
	v_mfma_f32_32x32x16_bf16 v[32:47], v[170:173], v[8:11], v[32:47]
	global_load_dwordx4 v[8:11], v[18:19], off offset:128
	s_waitcnt vmcnt(1)
	v_mfma_f32_32x32x16_bf16 v[48:63], v[138:141], v[12:15], v[48:63]
	v_mfma_f32_32x32x16_bf16 v[32:47], v[174:177], v[12:15], v[32:47]
	global_load_dwordx4 v[12:15], v[18:19], off offset:160
	s_waitcnt vmcnt(1)
	v_mfma_f32_32x32x16_bf16 v[48:63], v[142:145], v[8:11], v[48:63]
	v_mfma_f32_32x32x16_bf16 v[32:47], v[186:189], v[8:11], v[32:47]
	s_waitcnt vmcnt(0)
	v_mfma_f32_32x32x16_bf16 v[48:63], v[146:149], v[12:15], v[48:63]
	v_mfma_f32_32x32x16_bf16 v[32:47], v[190:193], v[12:15], v[32:47]
	v_add_co_u32_e32 v162, vcc, s17, v16
	s_or_b32 s4, s12, s23
	s_nop 0
	v_addc_co_u32_e32 v163, vcc, 0, v17, vcc
	global_load_dwordx4 v[8:11], v[162:163], off
	global_load_dwordx4 v[202:205], v[162:163], off offset:32
	s_waitcnt vmcnt(1)
	v_mfma_f32_32x32x16_bf16 v[16:31], v[0:3], v[8:11], 0
	s_waitcnt vmcnt(0)
	v_mfma_f32_32x32x16_bf16 v[16:31], v[130:133], v[202:205], v[16:31]
	global_load_dwordx4 v[130:133], v[162:163], off offset:64
	v_mfma_f32_32x32x16_bf16 v[0:15], v[4:7], v[8:11], 0
	v_mfma_f32_32x32x16_bf16 v[0:15], v[158:161], v[202:205], v[0:15]
	global_load_dwordx4 v[158:161], v[162:163], off offset:96
	s_waitcnt vmcnt(1)
	v_mfma_f32_32x32x16_bf16 v[16:31], v[134:137], v[130:133], v[16:31]
	global_load_dwordx4 v[134:137], v[162:163], off offset:160
	v_mfma_f32_32x32x16_bf16 v[0:15], v[170:173], v[130:133], v[0:15]
	global_load_dwordx4 v[130:133], v[162:163], off offset:128
	s_waitcnt vmcnt(2)
; #define LAS __attribute__((address_space(3)))
; #define MFMA32(a, b, c) __builtin_amdgcn_mfma_f32_32x32x16_bf16((a), (b), (c), 0, 0, 0)
; __device__ __forceinline__ void phase4_gmlp(const Args& a, LAS unsigned char* lds) {
;     ...
;             for (int ks = 0; ks < 2 * tt + 2; ++ks) {
;                 const bf16x8_t wf = *(const bf16x8_t*)(Wsp + ((size_t)g * 128 + 32 * tt + r) * 128 + 16 * ks + 8 * h);
;                 acc[0][tt] = MFMA32(zf[0][ks], wf, acc[0][tt]); acc[1][tt] = MFMA32(zf[1][ks], wf, acc[1][tt]);
;             } }
;         __builtin_amdgcn_sched_barrier(0);
; #pragma unroll
;         for (int hb = 0; hb < 2; ++hb) {
;             u32x4 zr[8];
; #pragma unroll
;             for (int it = 0; it < 8; ++it) zr[it] = __builtin_nontemporal_load((const u32x4*)(zu + (tok0 + (lane >> 3) + 8 * (8 * hb + it)) * 512 + g * 64 + (lane & 7) * 8));
; #pragma unroll
;             for (int it = 0; it < 8; ++it) { LAS unsigned char* p = tile + ((lane >> 3) + 8 * (8 * hb + it)) * G_TSTR + (lane & 7) * 16;
;                 *(LAS u32x2*)p = (u32x2){zr[it].x, zr[it].y}; *(LAS u32x2*)(p + 8) = (u32x2){zr[it].z, zr[it].w}; }
;         }
	v_mfma_f32_32x32x16_bf16 v[16:31], v[138:141], v[158:161], v[16:31]
	v_mfma_f32_32x32x16_bf16 v[0:15], v[174:177], v[158:161], v[0:15]
	s_waitcnt vmcnt(0)
	v_mfma_f32_32x32x16_bf16 v[16:31], v[142:145], v[130:133], v[16:31]
	v_mfma_f32_32x32x16_bf16 v[0:15], v[186:189], v[130:133], v[0:15]
	global_load_dwordx4 v[130:133], v[162:163], off offset:192
	v_mfma_f32_32x32x16_bf16 v[16:31], v[146:149], v[134:137], v[16:31]
	v_mfma_f32_32x32x16_bf16 v[0:15], v[190:193], v[134:137], v[0:15]
	global_load_dwordx4 v[134:137], v[162:163], off offset:224
	s_waitcnt vmcnt(1)
	v_mfma_f32_32x32x16_bf16 v[16:31], v[150:153], v[130:133], v[16:31]
	v_mfma_f32_32x32x16_bf16 v[0:15], v[194:197], v[130:133], v[0:15]
	s_waitcnt vmcnt(0)
	v_mfma_f32_32x32x16_bf16 v[16:31], v[154:157], v[134:137], v[16:31]
	v_mfma_f32_32x32x16_bf16 v[0:15], v[198:201], v[134:137], v[0:15]
	v_bfe_u32 v179, v178, 3, 3
	v_lshlrev_b32_e32 v128, 4, v178
	v_or_b32_e32 v160, s4, v179
	v_and_b32_e32 v128, 0x70, v128
	v_mov_b32_e32 v161, s13
	v_or_b32_e32 v158, 8, v160
	v_mov_b32_e32 v159, s13
	v_lshl_add_u64 v[162:163], s[8:9], 0, v[128:129]
	v_lshlrev_b64 v[130:131], 10, v[160:161]
	v_lshlrev_b64 v[132:133], 10, v[158:159]
	v_lshl_add_u64 v[130:131], v[162:163], 0, v[130:131]
	v_lshl_add_u64 v[132:133], v[162:163], 0, v[132:133]
	v_or_b32_e32 v154, 16, v160
	v_mov_b32_e32 v155, s13
	v_or_b32_e32 v148, 24, v160
	v_mov_b32_e32 v149, s13
	global_load_dwordx4 v[170:173], v[130:131], off nt
	global_load_dwordx4 v[174:177], v[132:133], off nt
	v_lshlrev_b64 v[130:131], 10, v[154:155]
	v_lshlrev_b64 v[132:133], 10, v[148:149]
	v_lshl_add_u64 v[130:131], v[162:163], 0, v[130:131]
	v_lshl_add_u64 v[132:133], v[162:163], 0, v[132:133]
	v_or_b32_e32 v142, 32, v160
	v_mov_b32_e32 v143, s13
	v_or_b32_e32 v136, 40, v160
	v_mov_b32_e32 v137, s13
	global_load_dwordx4 v[186:189], v[130:131], off nt
	global_load_dwordx4 v[190:193], v[132:133], off nt
	v_lshlrev_b64 v[130:131], 10, v[142:143]
	v_lshlrev_b64 v[132:133], 10, v[136:137]
	v_lshl_add_u64 v[130:131], v[162:163], 0, v[130:131]
	v_lshl_add_u64 v[132:133], v[162:163], 0, v[132:133]
	global_load_dwordx4 v[194:197], v[130:131], off nt
	global_load_dwordx4 v[198:201], v[132:133], off nt
	v_or_b32_e32 v132, 48, v160
	v_mov_b32_e32 v133, s13
	v_lshlrev_b64 v[130:131], 10, v[132:133]
	v_lshl_add_u64 v[134:135], v[162:163], 0, v[130:131]
	v_or_b32_e32 v130, 56, v160
	v_mov_b32_e32 v131, s13
	v_lshlrev_b64 v[138:139], 10, v[130:131]
	v_lshl_add_u64 v[138:139], v[162:163], 0, v[138:139]
	v_or_b32_e32 v156, 64, v160
	v_mov_b32_e32 v157, s13
	v_or_b32_e32 v152, 0x48, v160
	v_mov_b32_e32 v153, s13
	global_load_dwordx4 v[202:205], v[134:135], off nt
	global_load_dwordx4 v[206:209], v[138:139], off nt
	v_lshlrev_b64 v[134:135], 10, v[156:157]
	v_lshlrev_b64 v[138:139], 10, v[152:153]
	v_lshl_add_u64 v[134:135], v[162:163], 0, v[134:135]
	v_lshl_add_u64 v[138:139], v[162:163], 0, v[138:139]
	v_or_b32_e32 v150, 0x50, v160
	v_mov_b32_e32 v151, s13
	v_or_b32_e32 v146, 0x58, v160
	v_mov_b32_e32 v147, s13
	global_load_dwordx4 v[210:213], v[134:135], off nt
	global_load_dwordx4 v[214:217], v[138:139], off nt
	v_lshlrev_b64 v[134:135], 10, v[150:151]
	v_lshlrev_b64 v[138:139], 10, v[146:147]
	v_lshl_add_u64 v[134:135], v[162:163], 0, v[134:135]
	v_lshl_add_u64 v[138:139], v[162:163], 0, v[138:139]
	v_or_b32_e32 v144, 0x60, v160
	v_mov_b32_e32 v145, s13
	v_or_b32_e32 v140, 0x68, v160
	v_mov_b32_e32 v141, s13
	global_load_dwordx4 v[218:221], v[134:135], off nt
	global_load_dwordx4 v[222:225], v[138:139], off nt
	v_lshlrev_b64 v[134:135], 10, v[144:145]
	v_lshlrev_b64 v[138:139], 10, v[140:141]
	v_lshl_add_u64 v[134:135], v[162:163], 0, v[134:135]
	v_lshl_add_u64 v[138:139], v[162:163], 0, v[138:139]
	global_load_dwordx4 v[226:229], v[134:135], off nt
	global_load_dwordx4 v[230:233], v[138:139], off nt
	v_or_b32_e32 v138, 0x70, v160
	v_mov_b32_e32 v139, s13
	v_lshlrev_b64 v[134:135], 10, v[138:139]
	v_lshl_add_u64 v[134:135], v[162:163], 0, v[134:135]
	global_load_dwordx4 v[234:237], v[134:135], off nt
	v_or_b32_e32 v134, 0x78, v160
	v_mov_b32_e32 v135, s13
	v_lshlrev_b64 v[238:239], 10, v[134:135]
	v_lshl_add_u64 v[162:163], v[162:163], 0, v[238:239]
	global_load_dwordx4 v[238:241], v[162:163], off nt
	v_add_u32_e32 v180, s14, v128
	v_mad_u32_u24 v162, v179, s18, v180
	v_add_u32_e32 v163, 0x880, v162
	v_readlane_b32 s36, v254, 8
	v_readlane_b32 s40, v254, 12
	v_readlane_b32 s41, v254, 13
	v_add_u32_e32 v185, s14, v182
	s_waitcnt vmcnt(15)
	ds_write2_b64 v162, v[170:171], v[172:173] offset1:1
	s_waitcnt vmcnt(14)
	ds_write2_b64 v162, v[174:175], v[176:177] offset0:136 offset1:137
	v_cmp_lt_i32_e32 vcc, v167, v168
	v_readlane_b32 s37, v254, 9
	v_readlane_b32 s38, v254, 10
	v_cndmask_b32_e32 v182, v166, v167, vcc
	v_lshlrev_b32_e32 v182, 2, v182
	v_cmp_gt_u32_e32 vcc, 32, v183
	v_readlane_b32 s39, v254, 11
	s_waitcnt vmcnt(13)
	ds_write2_b64 v163, v[186:187], v[188:189] offset1:1
	v_add_u32_e32 v163, 0xcc0, v162
	v_add_u32_e32 v162, 0x1100, v162
	s_waitcnt vmcnt(12)
	ds_write2_b64 v163, v[190:191], v[192:193] offset1:1
	v_mov_b32_e32 v163, v129
	s_waitcnt vmcnt(11)
	ds_write2_b64 v162, v[194:195], v[196:197] offset1:1
	v_mad_u32_u24 v162, v179, s18, v164
	v_add_u32_e32 v177, v180, v162
	v_mad_u32_u24 v162, v179, s18, v165
	v_add_u32_e32 v173, v180, v162
	v_add_u32_e32 v176, 0x880, v177
	v_add_u32_e32 v175, 0xcc0, v177
	v_add_u32_e32 v174, 0x1100, v177
	v_add_u32_e32 v172, 0x880, v173
	v_add_u32_e32 v171, 0xcc0, v173
	v_add_u32_e32 v170, 0x1100, v173
	v_add_u32_e32 v178, 0x1540, v173
	s_waitcnt vmcnt(10)
	ds_write2_b64 v177, v[198:199], v[200:201] offset1:1
	s_waitcnt vmcnt(9)
; #define LAS __attribute__((address_space(3)))
; __device__ __forceinline__ void phase4_gmlp(const Args& a, LAS unsigned char* lds) {
;     ...
;         asm volatile("s_waitcnt lgkmcnt(0)" ::: "memory");
; #pragma unroll
;         for (int tt = 0; tt < 4; ++tt) {
;             const int tl = 32 * tt + r;
;             const float bias = sp_b[g * 128 + tl];
;             float ss = 0.f;
; #pragma unroll
;             for (int dt = 0; dt < 2; ++dt)
; #pragma unroll
;                 for (int ap = 0; ap < 4; ++ap) {
;                     const u32x2 zz = *(const LAS u32x2*)(tile + tl * G_TSTR + (32 * dt + 8 * ap + 4 * h) * 2);
;                     const float z0 = __uint_as_float(zz.x << 16), z1 = __uint_as_float(zz.x & 0xffff0000u), z2 = __uint_as_float(zz.y << 16), z3 = __uint_as_float(zz.y & 0xffff0000u);
;                     float v0 = z0 * (acc[dt][tt][4 * ap] + bias), v1 = z1 * (acc[dt][tt][4 * ap + 1] + bias), v2 = z2 * (acc[dt][tt][4 * ap + 2] + bias), v3 = z3 * (acc[dt][tt][4 * ap + 3] + bias);
;                     acc[dt][tt][4 * ap] = v0; acc[dt][tt][4 * ap + 1] = v1; acc[dt][tt][4 * ap + 2] = v2; acc[dt][tt][4 * ap + 3] = v3;
;                     ss += (v0 * v0 + v1 * v1) + (v2 * v2 + v3 * v3);
;                 }
;             ss += __shfl_xor(ss, 32);
;             if (h == 0) SSQ2[g * 128 + tl] = ss;
;         }
	ds_write2_b64 v177, v[202:203], v[204:205] offset0:136 offset1:137
	s_waitcnt vmcnt(8)
	ds_write2_b64 v176, v[206:207], v[208:209] offset1:1
	v_or_b32_e32 v162, s15, v181
	v_lshl_add_u64 v[186:187], v[162:163], 2, s[40:41]
	v_mad_u32_u24 v163, v181, s18, v185
	v_readlane_b32 s42, v254, 14
	v_readlane_b32 s43, v254, 15
	v_readlane_b32 s44, v254, 16
	v_readlane_b32 s45, v254, 17
	s_waitcnt vmcnt(7)
	ds_write2_b64 v175, v[210:211], v[212:213] offset1:1
	s_waitcnt vmcnt(6)
	ds_write2_b64 v174, v[214:215], v[216:217] offset1:1
	s_waitcnt vmcnt(5)
	ds_write2_b64 v173, v[218:219], v[220:221] offset1:1
	s_waitcnt vmcnt(4)
	ds_write2_b64 v173, v[222:223], v[224:225] offset0:136 offset1:137
	v_readlane_b32 s46, v254, 18
	v_readlane_b32 s47, v254, 19
	v_readlane_b32 s48, v254, 20
	s_waitcnt vmcnt(3)
	ds_write2_b64 v172, v[226:227], v[228:229] offset1:1
	s_waitcnt vmcnt(2)
	ds_write2_b64 v171, v[230:231], v[232:233] offset1:1
	v_readlane_b32 s49, v254, 21
	v_readlane_b32 s50, v254, 22
	v_readlane_b32 s51, v254, 23
	s_waitcnt vmcnt(1)
	ds_write2_b64 v170, v[234:235], v[236:237] offset1:1
	s_waitcnt vmcnt(0)
	ds_write2_b64 v178, v[238:239], v[240:241] offset1:1
	s_waitcnt lgkmcnt(0)
	ds_read2_b64 v[186:189], v163 offset1:2
	ds_read2_b64 v[190:193], v163 offset0:4 offset1:6
	ds_read2_b64 v[194:197], v163 offset0:8 offset1:10
	s_waitcnt lgkmcnt(2)
	v_lshlrev_b32_e32 v200, 16, v186
	v_and_b32_e32 v201, 0xffff0000, v186
	v_lshlrev_b32_e32 v186, 16, v187
	v_and_b32_e32 v187, 0xffff0000, v187
	v_lshlrev_b32_e32 v202, 16, v188
	v_and_b32_e32 v203, 0xffff0000, v188
	v_lshlrev_b32_e32 v188, 16, v189
	v_and_b32_e32 v189, 0xffff0000, v189
	s_waitcnt lgkmcnt(1)
	v_lshlrev_b32_e32 v204, 16, v190
	v_and_b32_e32 v205, 0xffff0000, v190
	v_lshlrev_b32_e32 v190, 16, v191
	v_and_b32_e32 v191, 0xffff0000, v191
	v_lshlrev_b32_e32 v206, 16, v192
	v_and_b32_e32 v207, 0xffff0000, v192
	v_lshlrev_b32_e32 v192, 16, v193
	v_and_b32_e32 v193, 0xffff0000, v193
	s_waitcnt lgkmcnt(0)
	v_lshlrev_b32_e32 v208, 16, v194
	v_and_b32_e32 v209, 0xffff0000, v194
	s_waitcnt vmcnt(0)
	v_pk_add_f32 v[114:115], v[114:115], v[242:243] op_sel_hi:[1,0]
	v_pk_add_f32 v[214:215], v[124:125], v[242:243] op_sel_hi:[1,0]
	v_pk_mul_f32 v[124:125], v[114:115], v[186:187]
	v_lshlrev_b32_e32 v186, 16, v195
	v_and_b32_e32 v187, 0xffff0000, v195
	v_pk_add_f32 v[98:99], v[98:99], v[242:243] op_sel_hi:[1,0]
	v_pk_add_f32 v[100:101], v[100:101], v[242:243] op_sel_hi:[1,0]
	v_pk_mul_f32 v[98:99], v[98:99], v[186:187]
	v_lshlrev_b32_e32 v186, 16, v196
	v_and_b32_e32 v187, 0xffff0000, v196
	v_lshlrev_b32_e32 v196, 16, v197
	v_and_b32_e32 v197, 0xffff0000, v197
	v_pk_add_f32 v[102:103], v[102:103], v[242:243] op_sel_hi:[1,0]
	v_pk_add_f32 v[116:117], v[116:117], v[242:243] op_sel_hi:[1,0]
	v_pk_add_f32 v[118:119], v[118:119], v[242:243] op_sel_hi:[1,0]
	v_pk_add_f32 v[210:211], v[120:121], v[242:243] op_sel_hi:[1,0]
	v_pk_add_f32 v[212:213], v[122:123], v[242:243] op_sel_hi:[1,0]
	v_pk_mul_f32 v[100:101], v[100:101], v[186:187]
	v_pk_mul_f32 v[102:103], v[102:103], v[196:197]
	v_pk_add_f32 v[112:113], v[112:113], v[242:243] op_sel_hi:[1,0]
	v_pk_mul_f32 v[122:123], v[116:117], v[202:203]
	v_pk_mul_f32 v[120:121], v[118:119], v[188:189]
	v_pk_mul_f32 v[118:119], v[210:211], v[204:205]
	v_pk_mul_f32 v[116:117], v[212:213], v[190:191]
	v_pk_mul_f32 v[114:115], v[214:215], v[206:207]
	v_pk_mul_f32 v[196:197], v[100:101], v[100:101]
	v_pk_mul_f32 v[214:215], v[102:103], v[102:103]
	v_pk_add_f32 v[216:217], v[126:127], v[242:243] op_sel_hi:[1,0]
	v_pk_mul_f32 v[126:127], v[112:113], v[200:201]
	v_pk_mul_f32 v[204:205], v[118:119], v[118:119]
	v_pk_mul_f32 v[206:207], v[116:117], v[116:117]
	ds_read2_b64 v[186:189], v163 offset0:12 offset1:14
	v_add_f32_e32 v163, v214, v215
	v_add_f32_e32 v196, v196, v197
	v_pk_mul_f32 v[112:113], v[216:217], v[192:193]
	v_pk_mul_f32 v[190:191], v[126:127], v[126:127]
	v_pk_mul_f32 v[192:193], v[124:125], v[124:125]
	v_pk_mul_f32 v[200:201], v[122:123], v[122:123]
	v_pk_mul_f32 v[202:203], v[120:121], v[120:121]
	v_add_f32_e32 v163, v196, v163
	v_add_f32_e32 v196, v206, v207
	v_add_f32_e32 v197, v204, v205
	v_add_f32_e32 v196, v197, v196
	v_add_f32_e32 v197, v202, v203
	v_add_f32_e32 v200, v200, v201
	v_add_f32_e32 v192, v192, v193
	v_add_f32_e32 v190, v190, v191
	v_pk_mul_f32 v[210:211], v[114:115], v[114:115]
	v_pk_mul_f32 v[212:213], v[112:113], v[112:113]
	v_pk_add_f32 v[96:97], v[96:97], v[242:243] op_sel_hi:[1,0]
	v_add_f32_e32 v197, v200, v197
	v_add_f32_e32 v190, v190, v192
	v_pk_mul_f32 v[96:97], v[96:97], v[208:209]
	v_add_f32_e32 v190, v190, v197
	v_add_f32_e32 v191, v212, v213
	v_add_f32_e32 v192, v210, v211
	v_pk_mul_f32 v[194:195], v[96:97], v[96:97]
	v_pk_mul_f32 v[208:209], v[98:99], v[98:99]
	v_add_f32_e32 v190, v190, v196
	v_add_f32_e32 v191, v192, v191
	s_waitcnt lgkmcnt(0)
	v_lshlrev_b32_e32 v216, 16, v186
	v_and_b32_e32 v217, 0xffff0000, v186
	v_pk_add_f32 v[104:105], v[104:105], v[242:243] op_sel_hi:[1,0]
	v_lshlrev_b32_e32 v186, 16, v187
	v_and_b32_e32 v187, 0xffff0000, v187
	v_pk_add_f32 v[106:107], v[106:107], v[242:243] op_sel_hi:[1,0]
	v_add_f32_e32 v190, v190, v191
	v_add_f32_e32 v191, v208, v209
	v_add_f32_e32 v192, v194, v195
	v_pk_mul_f32 v[104:105], v[104:105], v[216:217]
	v_pk_mul_f32 v[106:107], v[106:107], v[186:187]
	v_add_f32_e32 v191, v192, v191
	v_pk_mul_f32 v[186:187], v[104:105], v[104:105]
	v_pk_mul_f32 v[216:217], v[106:107], v[106:107]
	v_lshlrev_b32_e32 v218, 16, v188
	v_and_b32_e32 v219, 0xffff0000, v188
	v_pk_add_f32 v[108:109], v[108:109], v[242:243] op_sel_hi:[1,0]
	v_lshlrev_b32_e32 v188, 16, v189
	v_and_b32_e32 v189, 0xffff0000, v189
	v_pk_add_f32 v[110:111], v[110:111], v[242:243] op_sel_hi:[1,0]
	v_add_f32_e32 v190, v190, v191
	v_pk_mul_f32 v[108:109], v[108:109], v[218:219]
	v_pk_mul_f32 v[110:111], v[110:111], v[188:189]
	v_add_f32_e32 v163, v190, v163
	v_add_f32_e32 v190, v216, v217
	v_add_f32_e32 v186, v186, v187
	v_pk_mul_f32 v[188:189], v[108:109], v[108:109]
	v_pk_mul_f32 v[198:199], v[110:111], v[110:111]
	v_add_f32_e32 v186, v186, v190
	v_add_f32_e32 v163, v163, v186
	v_add_f32_e32 v186, v198, v199
	v_add_f32_e32 v187, v188, v189
	v_add_f32_e32 v186, v187, v186
	v_add_f32_e32 v163, v163, v186
	ds_bpermute_b32 v186, v182, v163
	s_and_saveexec_b64 s[12:13], vcc
	s_cbranch_execz .LBB0_880
	v_lshl_add_u32 v162, v162, 2, 0
	s_waitcnt lgkmcnt(0)
	v_add_f32_e32 v163, v163, v186
	v_add_u32_e32 v162, 0x22000, v162
	ds_write_b32 v162, v163
